# scan S1 C*B^T block: a_cs column reads of the first two column groups and the row value issued up front
# baseline (speedup 1.0000x reference)
; DI u32x4 pack8(const float (&f)[8]) { u32x4 r; r[0] = pk2(f[0], f[1]); r[1] = pk2(f[2], f[3]); r[2] = pk2(f[4], f[5]); r[3] = pk2(f[6], f[7]); return r; }
; DI void ssd_scan_phase(bf16_t* P, const bf16_t* BT, const bf16_t* Cc, const bf16_t* CB, const float* dt, const float* acs,
;                        const float* cw, const float* cb, const float* Dp, char* lds, bool dry, int mode, float* Sbuf) {
;     ...
;         const f32x4 a0 = *(const f32x4*)(cAcs + cch * 8), a1 = *(const f32x4*)(cAcs + cch * 8 + 4);
;         const float L2E = 1.44269504f;
;         const float as[8] = {a0[0] * L2E, a0[1] * L2E, a0[2] * L2E, a0[3] * L2E, a1[0] * L2E, a1[1] * L2E, a1[2] * L2E, a1[3] * L2E};
; #pragma unroll
;         for (int j = 0; j < 4; ++j) {
;           const int r = r0 + 32 * j;
;           *(u32x4*)(sBT + swz128(r, cch)) = rB[j];
;           if (mode == 0) {
;             *(u32x4*)(sC + swz128(r, cch)) = rC[j];
;             float f[8]; unpack8(rCB[j], f);
;             const float el = cAcs[r] * L2E;
;             const int lim = r - cch * 8;
; #pragma unroll
;             for (int e = 0; e < 8; ++e) f[e] = (e <= lim) ? f[e] * __builtin_amdgcn_exp2f(el - as[e]) : 0.f;
;             *(u32x4*)(sCBL + swz128(r, cch)) = pack8(f);
.Ls1n:
	v_bitop3_b32 v30, v29, v34, 15 bitop3:0x6c
	v_lshlrev_b32_e32 v30, 4, v30
	v_lshl_add_u32 v33, v29, 8, v30
	v_add_u32_e32 v35, 0x10000, v33
	v_lshrrev_b32_e32 v20, 2, v200
	v_sub_u32_e32 v20, 0x7f, v20
	v_and_b32_e32 v21, 3, v200
	v_lshl_add_u32 v22, v20, 2, s88
	ds_read_b32 v32, v22
	v_lshl_add_u32 v23, v21, 5, s88
	v_lshlrev_b32_e32 v24, 8, v20
	v_and_b32_e32 v25, 15, v20
	v_lshlrev_b32_e32 v26, 3, v21
	v_sub_u32_e32 v26, v20, v26
	ds_read_b128 v[36:39], v23
	ds_read_b128 v[42:45], v23 offset:16
	ds_read_b128 v[28:31], v23 offset:128
	ds_read_b128 v[48:51], v23 offset:144
	v_readfirstlane_b32 s78, v200
	s_lshr_b32 s78, s78, 6
	s_cmp_lg_u64 s[42:43], 0
	s_cbranch_scc1 .Ls1n_w47_0
	s_waitcnt vmcnt(17)
	s_branch .Ls1n_wd_0

; DI u32x4 pack8(const float (&f)[8]) { u32x4 r; r[0] = pk2(f[0], f[1]); r[1] = pk2(f[2], f[3]); r[2] = pk2(f[4], f[5]); r[3] = pk2(f[6], f[7]); return r; }
; DI void ssd_scan_phase(bf16_t* P, const bf16_t* BT, const bf16_t* Cc, const bf16_t* CB, const float* dt, const float* acs,
;                        const float* cw, const float* cb, const float* Dp, char* lds, bool dry, int mode, float* Sbuf) {
;     ...
;         for (int j = 0; j < 4; ++j) {
;           const int r = r0 + 32 * j;
;           *(u32x4*)(sBT + swz128(r, cch)) = rB[j];
;           if (mode == 0) {
;             *(u32x4*)(sC + swz128(r, cch)) = rC[j];
;             float f[8]; unpack8(rCB[j], f);
;             const float el = cAcs[r] * L2E;
;             const int lim = r - cch * 8;
; #pragma unroll
;             for (int e = 0; e < 8; ++e) f[e] = (e <= lim) ? f[e] * __builtin_amdgcn_exp2f(el - as[e]) : 0.f;
;             *(u32x4*)(sCBL + swz128(r, cch)) = pack8(f);
;           }
.Ls1n_wd_0:
	ds_write_b128 v35, v[60:63]
	ds_write_b128 v33, v[52:55] offset:32768
	s_add_i32 s79, s78, 0
	s_cmp_gt_i32 s79, 7
	s_cbranch_scc1 .Ls1n_skip_0
	s_waitcnt lgkmcnt(0)
	v_mul_f32_e32 v36, 0x3fb8aa3b, v36
	v_mul_f32_e32 v37, 0x3fb8aa3b, v37
	v_mul_f32_e32 v38, 0x3fb8aa3b, v38
	v_mul_f32_e32 v39, 0x3fb8aa3b, v39
	v_mul_f32_e32 v42, 0x3fb8aa3b, v42
	v_mul_f32_e32 v43, 0x3fb8aa3b, v43
	v_mul_f32_e32 v44, 0x3fb8aa3b, v44
	v_mul_f32_e32 v45, 0x3fb8aa3b, v45
	v_fma_f32 v36, v32, s29, -v36
	v_fma_f32 v37, v32, s29, -v37
	v_fma_f32 v38, v32, s29, -v38
	v_fma_f32 v39, v32, s29, -v39
	v_fma_f32 v42, v32, s29, -v42
	v_fma_f32 v43, v32, s29, -v43
	v_fma_f32 v44, v32, s29, -v44
	v_fma_f32 v45, v32, s29, -v45
	v_exp_f32_e32 v36, v36
	v_exp_f32_e32 v37, v37
	v_exp_f32_e32 v38, v38
	v_exp_f32_e32 v39, v39
	v_exp_f32_e32 v42, v42
	v_exp_f32_e32 v43, v43
	v_exp_f32_e32 v44, v44
	v_exp_f32_e32 v45, v45
	v_lshlrev_b32_e32 v46, 16, v56
	v_and_b32_e32 v47, 0xffff0000, v56
	v_pk_mul_f32 v[36:37], v[36:37], v[46:47]
	v_lshlrev_b32_e32 v46, 16, v57
	v_and_b32_e32 v47, 0xffff0000, v57
	v_pk_mul_f32 v[38:39], v[38:39], v[46:47]
	v_lshlrev_b32_e32 v46, 16, v58
	v_and_b32_e32 v47, 0xffff0000, v58
	v_pk_mul_f32 v[42:43], v[42:43], v[46:47]
	v_lshlrev_b32_e32 v46, 16, v59
	v_and_b32_e32 v47, 0xffff0000, v59
	v_pk_mul_f32 v[44:45], v[44:45], v[46:47]
	s_cmp_lt_i32 s79, 6
	s_cbranch_scc1 .Ls1n_nomask_0
	v_mov_b32_e32 v27, v26
	v_cmp_le_i32_e32 vcc, 0, v27
	s_nop 1
	v_cndmask_b32_e32 v36, 0, v36, vcc
	v_cmp_le_i32_e32 vcc, 1, v27
	s_nop 1
	v_cndmask_b32_e32 v37, 0, v37, vcc
	v_cmp_le_i32_e32 vcc, 2, v27
	s_nop 1
	v_cndmask_b32_e32 v38, 0, v38, vcc
	v_cmp_le_i32_e32 vcc, 3, v27
	s_nop 1
	v_cndmask_b32_e32 v39, 0, v39, vcc
	v_cmp_le_i32_e32 vcc, 4, v27
	s_nop 1
	v_cndmask_b32_e32 v42, 0, v42, vcc
	v_cmp_le_i32_e32 vcc, 5, v27
	s_nop 1
	v_cndmask_b32_e32 v43, 0, v43, vcc
	v_cmp_le_i32_e32 vcc, 6, v27
	s_nop 1
	v_cndmask_b32_e32 v44, 0, v44, vcc
	v_cmp_le_i32_e32 vcc, 7, v27
	s_nop 1
	v_cndmask_b32_e32 v45, 0, v45, vcc

; DI u32x4 pack8(const float (&f)[8]) { u32x4 r; r[0] = pk2(f[0], f[1]); r[1] = pk2(f[2], f[3]); r[2] = pk2(f[4], f[5]); r[3] = pk2(f[6], f[7]); return r; }
; DI void ssd_scan_phase(bf16_t* P, const bf16_t* BT, const bf16_t* Cc, const bf16_t* CB, const float* dt, const float* acs,
;                        const float* cw, const float* cb, const float* Dp, char* lds, bool dry, int mode, float* Sbuf) {
;     ...
;         for (int j = 0; j < 4; ++j) {
;           const int r = r0 + 32 * j;
;           *(u32x4*)(sBT + swz128(r, cch)) = rB[j];
;           if (mode == 0) {
;             *(u32x4*)(sC + swz128(r, cch)) = rC[j];
;             float f[8]; unpack8(rCB[j], f);
;             const float el = cAcs[r] * L2E;
;             const int lim = r - cch * 8;
; #pragma unroll
;             for (int e = 0; e < 8; ++e) f[e] = (e <= lim) ? f[e] * __builtin_amdgcn_exp2f(el - as[e]) : 0.f;
;             *(u32x4*)(sCBL + swz128(r, cch)) = pack8(f);
;           }
.Ls1n_wd_1:
	ds_write_b128 v35, v[76:79] offset:8192
	ds_write_b128 v33, v[64:67] offset:40960
	s_add_i32 s79, s78, 2
	s_cmp_gt_i32 s79, 7
	s_cbranch_scc1 .Ls1n_skip_1
	s_waitcnt lgkmcnt(0)
	v_mul_f32_e32 v28, 0x3fb8aa3b, v28
	v_mul_f32_e32 v29, 0x3fb8aa3b, v29
	v_mul_f32_e32 v30, 0x3fb8aa3b, v30
	v_mul_f32_e32 v31, 0x3fb8aa3b, v31
	v_mul_f32_e32 v48, 0x3fb8aa3b, v48
	v_mul_f32_e32 v49, 0x3fb8aa3b, v49
	v_mul_f32_e32 v50, 0x3fb8aa3b, v50
	v_mul_f32_e32 v51, 0x3fb8aa3b, v51
	v_fma_f32 v28, v32, s29, -v28
	v_fma_f32 v29, v32, s29, -v29
	v_fma_f32 v30, v32, s29, -v30
	v_fma_f32 v31, v32, s29, -v31
	v_fma_f32 v48, v32, s29, -v48
	v_fma_f32 v49, v32, s29, -v49
	v_fma_f32 v50, v32, s29, -v50
	v_fma_f32 v51, v32, s29, -v51
	v_exp_f32_e32 v28, v28
	v_exp_f32_e32 v29, v29
	v_exp_f32_e32 v30, v30
	v_exp_f32_e32 v31, v31
	v_exp_f32_e32 v48, v48
	v_exp_f32_e32 v49, v49
	v_exp_f32_e32 v50, v50
	v_exp_f32_e32 v51, v51
	v_lshlrev_b32_e32 v46, 16, v68
	v_and_b32_e32 v47, 0xffff0000, v68
	v_pk_mul_f32 v[28:29], v[28:29], v[46:47]
	v_lshlrev_b32_e32 v46, 16, v69
	v_and_b32_e32 v47, 0xffff0000, v69
	v_pk_mul_f32 v[30:31], v[30:31], v[46:47]
	v_lshlrev_b32_e32 v46, 16, v70
	v_and_b32_e32 v47, 0xffff0000, v70
	v_pk_mul_f32 v[48:49], v[48:49], v[46:47]
	v_lshlrev_b32_e32 v46, 16, v71
	v_and_b32_e32 v47, 0xffff0000, v71
	v_pk_mul_f32 v[50:51], v[50:51], v[46:47]
	s_cmp_lt_i32 s79, 6
	s_cbranch_scc1 .Ls1n_nomask_1
	v_add_u32_e32 v27, -32, v26
	v_cmp_le_i32_e32 vcc, 0, v27
	s_nop 1
	v_cndmask_b32_e32 v28, 0, v28, vcc
	v_cmp_le_i32_e32 vcc, 1, v27
	s_nop 1
	v_cndmask_b32_e32 v29, 0, v29, vcc
	v_cmp_le_i32_e32 vcc, 2, v27
	s_nop 1
	v_cndmask_b32_e32 v30, 0, v30, vcc
	v_cmp_le_i32_e32 vcc, 3, v27
	s_nop 1
	v_cndmask_b32_e32 v31, 0, v31, vcc
	v_cmp_le_i32_e32 vcc, 4, v27
	s_nop 1
	v_cndmask_b32_e32 v48, 0, v48, vcc
	v_cmp_le_i32_e32 vcc, 5, v27
	s_nop 1
	v_cndmask_b32_e32 v49, 0, v49, vcc
	v_cmp_le_i32_e32 vcc, 6, v27
	s_nop 1
	v_cndmask_b32_e32 v50, 0, v50, vcc
	v_cmp_le_i32_e32 vcc, 7, v27
	s_nop 1
	v_cndmask_b32_e32 v51, 0, v51, vcc
.Ls1n_nomask_1:
	v_cvt_pk_bf16_f32 v36, v28, v29
	v_cvt_pk_bf16_f32 v37, v30, v31
	v_cvt_pk_bf16_f32 v38, v48, v49
	v_cvt_pk_bf16_f32 v39, v50, v51
	v_add_u32_e32 v22, 4, v21
	v_xor_b32_e32 v22, v22, v25
	v_lshl_add_u32 v22, v22, 4, v24
	ds_write_b128 v22, v[36:39]

; DI u32x4 pack8(const float (&f)[8]) { u32x4 r; r[0] = pk2(f[0], f[1]); r[1] = pk2(f[2], f[3]); r[2] = pk2(f[4], f[5]); r[3] = pk2(f[6], f[7]); return r; }
; DI void ssd_scan_phase(bf16_t* P, const bf16_t* BT, const bf16_t* Cc, const bf16_t* CB, const float* dt, const float* acs,
;                        const float* cw, const float* cb, const float* Dp, char* lds, bool dry, int mode, float* Sbuf) {
;     ...
;         for (int j = 0; j < 4; ++j) {
;           const int r = r0 + 32 * j;
;           *(u32x4*)(sBT + swz128(r, cch)) = rB[j];
;           if (mode == 0) {
;             *(u32x4*)(sC + swz128(r, cch)) = rC[j];
;             float f[8]; unpack8(rCB[j], f);
;             const float el = cAcs[r] * L2E;
;             const int lim = r - cch * 8;
; #pragma unroll
;             for (int e = 0; e < 8; ++e) f[e] = (e <= lim) ? f[e] * __builtin_amdgcn_exp2f(el - as[e]) : 0.f;
;             *(u32x4*)(sCBL + swz128(r, cch)) = pack8(f);
;           }
.Ls1n_wd_2:
	ds_write_b128 v35, v[92:95] offset:16384
	ds_write_b128 v33, v[72:75] offset:49152
	s_add_i32 s79, s78, 4
	s_cmp_gt_i32 s79, 7
	s_cbranch_scc1 .Ls1n_skip_2
	ds_read_b128 v[36:39], v23 offset:256
	ds_read_b128 v[42:45], v23 offset:272
	s_waitcnt lgkmcnt(0)
	v_mul_f32_e32 v36, 0x3fb8aa3b, v36
	v_mul_f32_e32 v37, 0x3fb8aa3b, v37
	v_mul_f32_e32 v38, 0x3fb8aa3b, v38
	v_mul_f32_e32 v39, 0x3fb8aa3b, v39
	v_mul_f32_e32 v42, 0x3fb8aa3b, v42
	v_mul_f32_e32 v43, 0x3fb8aa3b, v43
	v_mul_f32_e32 v44, 0x3fb8aa3b, v44
	v_mul_f32_e32 v45, 0x3fb8aa3b, v45
	v_fma_f32 v36, v32, s29, -v36
	v_fma_f32 v37, v32, s29, -v37
	v_fma_f32 v38, v32, s29, -v38
	v_fma_f32 v39, v32, s29, -v39
	v_fma_f32 v42, v32, s29, -v42
	v_fma_f32 v43, v32, s29, -v43
	v_fma_f32 v44, v32, s29, -v44
	v_fma_f32 v45, v32, s29, -v45
	v_exp_f32_e32 v36, v36
	v_exp_f32_e32 v37, v37
	v_exp_f32_e32 v38, v38
	v_exp_f32_e32 v39, v39
	v_exp_f32_e32 v42, v42
	v_exp_f32_e32 v43, v43
	v_exp_f32_e32 v44, v44
	v_exp_f32_e32 v45, v45
	v_lshlrev_b32_e32 v46, 16, v80
	v_and_b32_e32 v47, 0xffff0000, v80
	v_pk_mul_f32 v[36:37], v[36:37], v[46:47]
	v_lshlrev_b32_e32 v46, 16, v81
	v_and_b32_e32 v47, 0xffff0000, v81
	v_pk_mul_f32 v[38:39], v[38:39], v[46:47]
	v_lshlrev_b32_e32 v46, 16, v82
	v_and_b32_e32 v47, 0xffff0000, v82
	v_pk_mul_f32 v[42:43], v[42:43], v[46:47]
	v_lshlrev_b32_e32 v46, 16, v83
	v_and_b32_e32 v47, 0xffff0000, v83
	v_pk_mul_f32 v[44:45], v[44:45], v[46:47]
	s_cmp_lt_i32 s79, 6
	s_cbranch_scc1 .Ls1n_nomask_2
	v_add_u32_e32 v27, -64, v26
	v_cmp_le_i32_e32 vcc, 0, v27
	s_nop 1
	v_cndmask_b32_e32 v36, 0, v36, vcc
	v_cmp_le_i32_e32 vcc, 1, v27
	s_nop 1
	v_cndmask_b32_e32 v37, 0, v37, vcc
	v_cmp_le_i32_e32 vcc, 2, v27
	s_nop 1
	v_cndmask_b32_e32 v38, 0, v38, vcc
	v_cmp_le_i32_e32 vcc, 3, v27
	s_nop 1
	v_cndmask_b32_e32 v39, 0, v39, vcc
	v_cmp_le_i32_e32 vcc, 4, v27
	s_nop 1
	v_cndmask_b32_e32 v42, 0, v42, vcc
	v_cmp_le_i32_e32 vcc, 5, v27
	s_nop 1
	v_cndmask_b32_e32 v43, 0, v43, vcc
	v_cmp_le_i32_e32 vcc, 6, v27
	s_nop 1
	v_cndmask_b32_e32 v44, 0, v44, vcc
	v_cmp_le_i32_e32 vcc, 7, v27
	s_nop 1
	v_cndmask_b32_e32 v45, 0, v45, vcc

; DI u32x4 pack8(const float (&f)[8]) { u32x4 r; r[0] = pk2(f[0], f[1]); r[1] = pk2(f[2], f[3]); r[2] = pk2(f[4], f[5]); r[3] = pk2(f[6], f[7]); return r; }
; DI void ssd_scan_phase(bf16_t* P, const bf16_t* BT, const bf16_t* Cc, const bf16_t* CB, const float* dt, const float* acs,
;                        const float* cw, const float* cb, const float* Dp, char* lds, bool dry, int mode, float* Sbuf) {
;     ...
;         for (int j = 0; j < 4; ++j) {
;           const int r = r0 + 32 * j;
;           *(u32x4*)(sBT + swz128(r, cch)) = rB[j];
;           if (mode == 0) {
;             *(u32x4*)(sC + swz128(r, cch)) = rC[j];
;             float f[8]; unpack8(rCB[j], f);
;             const float el = cAcs[r] * L2E;
;             const int lim = r - cch * 8;
; #pragma unroll
;             for (int e = 0; e < 8; ++e) f[e] = (e <= lim) ? f[e] * __builtin_amdgcn_exp2f(el - as[e]) : 0.f;
;             *(u32x4*)(sCBL + swz128(r, cch)) = pack8(f);
;           }
.Ls1n_wd_3:
	ds_write_b128 v35, v[104:107] offset:24576
	ds_write_b128 v33, v[84:87] offset:57344
	s_add_i32 s79, s78, 6
	s_cmp_gt_i32 s79, 7
	s_cbranch_scc1 .Ls1n_skip_3
	ds_read_b128 v[36:39], v23 offset:384
	ds_read_b128 v[42:45], v23 offset:400
	s_waitcnt lgkmcnt(0)
	v_mul_f32_e32 v36, 0x3fb8aa3b, v36
	v_mul_f32_e32 v37, 0x3fb8aa3b, v37
	v_mul_f32_e32 v38, 0x3fb8aa3b, v38
	v_mul_f32_e32 v39, 0x3fb8aa3b, v39
	v_mul_f32_e32 v42, 0x3fb8aa3b, v42
	v_mul_f32_e32 v43, 0x3fb8aa3b, v43
	v_mul_f32_e32 v44, 0x3fb8aa3b, v44
	v_mul_f32_e32 v45, 0x3fb8aa3b, v45
	v_fma_f32 v36, v32, s29, -v36
	v_fma_f32 v37, v32, s29, -v37
	v_fma_f32 v38, v32, s29, -v38
	v_fma_f32 v39, v32, s29, -v39
	v_fma_f32 v42, v32, s29, -v42
	v_fma_f32 v43, v32, s29, -v43
	v_fma_f32 v44, v32, s29, -v44
	v_fma_f32 v45, v32, s29, -v45
	v_exp_f32_e32 v36, v36
	v_exp_f32_e32 v37, v37
	v_exp_f32_e32 v38, v38
	v_exp_f32_e32 v39, v39
	v_exp_f32_e32 v42, v42
	v_exp_f32_e32 v43, v43
	v_exp_f32_e32 v44, v44
	v_exp_f32_e32 v45, v45
	v_lshlrev_b32_e32 v46, 16, v88
	v_and_b32_e32 v47, 0xffff0000, v88
	v_pk_mul_f32 v[36:37], v[36:37], v[46:47]
	v_lshlrev_b32_e32 v46, 16, v89
	v_and_b32_e32 v47, 0xffff0000, v89
	v_pk_mul_f32 v[38:39], v[38:39], v[46:47]
	v_lshlrev_b32_e32 v46, 16, v90
	v_and_b32_e32 v47, 0xffff0000, v90
	v_pk_mul_f32 v[42:43], v[42:43], v[46:47]
	v_lshlrev_b32_e32 v46, 16, v91
	v_and_b32_e32 v47, 0xffff0000, v91
	v_pk_mul_f32 v[44:45], v[44:45], v[46:47]
	s_cmp_lt_i32 s79, 6
	s_cbranch_scc1 .Ls1n_nomask_3
	v_add_u32_e32 v27, -96, v26
	v_cmp_le_i32_e32 vcc, 0, v27
	s_nop 1
	v_cndmask_b32_e32 v36, 0, v36, vcc
	v_cmp_le_i32_e32 vcc, 1, v27
	s_nop 1
	v_cndmask_b32_e32 v37, 0, v37, vcc
	v_cmp_le_i32_e32 vcc, 2, v27
	s_nop 1
	v_cndmask_b32_e32 v38, 0, v38, vcc
	v_cmp_le_i32_e32 vcc, 3, v27
	s_nop 1
	v_cndmask_b32_e32 v39, 0, v39, vcc
	v_cmp_le_i32_e32 vcc, 4, v27
	s_nop 1
	v_cndmask_b32_e32 v42, 0, v42, vcc
	v_cmp_le_i32_e32 vcc, 5, v27
	s_nop 1
	v_cndmask_b32_e32 v43, 0, v43, vcc
	v_cmp_le_i32_e32 vcc, 6, v27
	s_nop 1
	v_cndmask_b32_e32 v44, 0, v44, vcc
	v_cmp_le_i32_e32 vcc, 7, v27
	s_nop 1
	v_cndmask_b32_e32 v45, 0, v45, vcc
